# small-GEMM phase: no vmcnt(0) drain between consecutive GEMMs (lora1, lora2, KV, Q exits)
# baseline (speedup 1.0000x reference)
; #define PG8_WAIT_V(n) asm volatile("s_waitcnt vmcnt(" #n ")" ::: "memory")
; #define PG8_BAR __builtin_amdgcn_s_barrier()
; template <class Epi, class Sched>
; DI void gemm_phase(LAS unsigned char* lds, const Gemm g, const Sched& S, const Epi& E) {
;     ...
;     PG8_WAIT_V(0);
;     if (wr == 0) PG8_BAR;
;     PG8_BAR;
.LBB0_449:
	v_readlane_b32 s2, v250, 16
	s_cmpk_gt_u32 s2, 0xff
	s_cbranch_scc1 .LBB0_451
	s_barrier

; #define PG8_WAIT_V(n) asm volatile("s_waitcnt vmcnt(" #n ")" ::: "memory")
; #define PG8_BAR __builtin_amdgcn_s_barrier()
; template <class Epi, class Sched>
; DI void gemm_phase(LAS unsigned char* lds, const Gemm g, const Sched& S, const Epi& E) {
;     ...
;     PG8_WAIT_V(0);
;     if (wr == 0) PG8_BAR;
;     PG8_BAR;
.LBB0_668:
	s_cmpk_gt_u32 s11, 0xff
	v_readlane_b32 s78, v251, 54
	s_cbranch_scc1 .LBB0_670
	s_barrier

; #define PG8_WAIT_V(n) asm volatile("s_waitcnt vmcnt(" #n ")" ::: "memory")
; #define PG8_BAR __builtin_amdgcn_s_barrier()
; template <class Epi, class Sched>
; DI void gemm_phase(LAS unsigned char* lds, const Gemm g, const Sched& S, const Epi& E) {
;     ...
;     PG8_WAIT_V(0);
;     if (wr == 0) PG8_BAR;
;     PG8_BAR;
.LBB0_760:
	v_readlane_b32 s58, v251, 55
	s_cmpk_gt_u32 s61, 0xff
	v_readlane_b32 s59, v251, 56
	v_readlane_b32 s78, v251, 54
	s_cbranch_scc1 .LBB0_762
	s_barrier
